# A-loop: rare diagonal-mask and rescale blocks moved out of line (hot path falls through, 1 taken branch per step instead of 3); mask-path MFMA-to-VALU pad restored to 12 states
# baseline (speedup 1.0000x reference)
; DI f32x16 mfma(bf16x8 a, bf16x8 b, f32x16 c) { return __builtin_amdgcn_mfma_f32_32x32x16_bf16(a, b, c, 0, 0, 0); }
; DI void diff_softmax_pv(const bf16x8 (&qf)[4], const u16* Ks, const u16* Vs, float& m, f32x4& ls0, f32x4& ls1, bf16x8 ones,
;                         f32x16 (&o)[2][2], float sl2, int dl, bool need_mask, bool first, int r, int h, int rs, const int (&lo)[4]) {
;     ...
;   const float nb = -sl2 * (float)dl - m;
; #pragma unroll
;   for (int i = 0; i < 16; ++i) {
;     const int ci = (i & 3) + 8 * (i >> 2);
;     b0[i] = fmaf(sl2, (float)ci, nb);
;     b1[i] = fmaf(sl2, (float)(ci + 32), nb);
;   }
;   {
;     __builtin_amdgcn_s_setprio(1);
;     f32x16 s0 = mfma(ldsv(Ks + lo[0]), qf[0], b0);
;     f32x16 s1 = mfma(ldsv(Ks + 32 * rs + lo[0]), qf[0], b1);
;     s0 = mfma(ldsv(Ks + lo[1]), qf[1], s0);
;     s1 = mfma(ldsv(Ks + 32 * rs + lo[1]), qf[1], s1);
;     __builtin_amdgcn_s_setprio(0);
;     if (need_mask) mask_causal(s0, s1, dl);
.LBB0_281:
	s_or_b64 exec, exec, s[2:3]
	v_cvt_f32_i32_e32 v66, v207
	s_and_b32 s2, s64, 0x2000
	v_lshl_add_u32 v211, s2, 1, v176
	v_lshl_add_u32 v213, v183, 1, v211
	v_lshl_add_u32 v212, v184, 1, v211
	v_fma_f32 v229, -v178, v66, -v204
	v_lshl_add_u32 v246, v185, 1, v211
	v_lshl_add_u32 v247, v186, 1, v211
	ds_read_b128 v[114:117], v213
	ds_read_b128 v[214:217], v213 offset:4096
	ds_read_b128 v[218:221], v212
	ds_read_b128 v[222:225], v212 offset:4096
	ds_read_b128 v[230:233], v246
	ds_read_b128 v[234:237], v246 offset:4096
	ds_read_b128 v[238:241], v247
	ds_read_b128 v[242:245], v247 offset:4096
	v_cmp_eq_u32_e64 s[38:39], 0, v208
	v_fma_f32 v66, 0, v178, v229
	v_add_f32_e32 v67, v178, v229
	v_fmamk_f32 v68, v178, 0x40000000, v229
	v_fmamk_f32 v69, v178, 0x40400000, v229
	v_fmamk_f32 v70, v178, 0x41000000, v229
	v_fmamk_f32 v71, v178, 0x41100000, v229
	v_fmamk_f32 v72, v178, 0x41200000, v229
	v_fmamk_f32 v73, v178, 0x41300000, v229
	v_fmamk_f32 v74, v178, 0x41800000, v229
	v_fmamk_f32 v75, v178, 0x41880000, v229
	v_fmamk_f32 v76, v178, 0x41900000, v229
	v_fmamk_f32 v77, v178, 0x41980000, v229
	v_fmamk_f32 v78, v178, 0x41c00000, v229
	v_fmamk_f32 v79, v178, 0x41c80000, v229
	v_fmamk_f32 v80, v178, 0x41d00000, v229
	v_fmamk_f32 v81, v178, 0x41d80000, v229
	v_fmamk_f32 v82, v178, 0x42000000, v229
	v_fmamk_f32 v83, v178, 0x42040000, v229
	v_fmamk_f32 v84, v178, 0x42080000, v229
	v_fmamk_f32 v85, v178, 0x420c0000, v229
	v_fmamk_f32 v86, v178, 0x42200000, v229
	v_fmamk_f32 v87, v178, 0x42240000, v229
	v_fmamk_f32 v88, v178, 0x42280000, v229
	v_fmamk_f32 v89, v178, 0x422c0000, v229
	v_fmamk_f32 v90, v178, 0x42400000, v229
	v_fmamk_f32 v91, v178, 0x42440000, v229
	v_fmamk_f32 v92, v178, 0x42480000, v229
	v_fmamk_f32 v93, v178, 0x424c0000, v229
	v_fmamk_f32 v94, v178, 0x42600000, v229
	v_fmamk_f32 v95, v178, 0x42640000, v229
	v_fmamk_f32 v96, v178, 0x42680000, v229
	v_fmamk_f32 v97, v178, 0x426c0000, v229
	s_setprio 1
	s_waitcnt lgkmcnt(6)
	v_mfma_f32_32x32x16_bf16 v[98:113], v[114:117], v[130:133], v[66:81]
	v_mfma_f32_32x32x16_bf16 v[114:129], v[214:217], v[130:133], v[82:97]
	s_waitcnt lgkmcnt(5)
	v_mfma_f32_32x32x16_bf16 v[98:113], v[218:221], v[134:137], v[98:113]
	s_waitcnt lgkmcnt(4)
	v_mfma_f32_32x32x16_bf16 v[114:129], v[222:225], v[134:137], v[114:129]
	s_setprio 0
	s_and_saveexec_b64 s[2:3], s[38:39]
	s_cbranch_execnz .Lmask0_ool

; DI void diff_softmax_pv(const bf16x8 (&qf)[4], const u16* Ks, const u16* Vs, float& m, f32x4& ls0, f32x4& ls1, bf16x8 ones,
;                         f32x16 (&o)[2][2], float sl2, int dl, bool need_mask, bool first, int r, int h, int rs, const int (&lo)[4]) {
;     ...
;     if (__any(first || !(ls0[0] <= 1.0e12f) || !(ls0[1] <= 1.0e12f) || !(ls1[0] <= 1.0e12f) || !(ls1[1] <= 1.0e12f))) {
;       float tmax = -INFINITY;
.LBB0_287:
	s_or_b64 exec, exec, s[2:3]
	v_cndmask_b32_e64 v214, 0, 1, s[44:45]
	v_cmp_ne_u32_e32 vcc, 0, v214
	s_cbranch_vccnz .Lresc_ool

; DI void mask_causal(f32x16& s0, f32x16& s1, int dl) {
; #pragma unroll
;   for (int i = 0; i < 16; ++i) {
;     const int ci = (i & 3) + 8 * (i >> 2);
;     s0[i] = (ci <= dl) ? s0[i] : -INFINITY;
;     s1[i] = (ci + 32 <= dl) ? s1[i] : -INFINITY;
;   }
; }
.Lmask0_ool:
	v_cmp_lt_i32_e32 vcc, -1, v207
	s_nop 5
	v_cndmask_b32_e32 v98, v199, v98, vcc
	v_cmp_lt_i32_e32 vcc, 31, v207
	s_nop 1
	v_cndmask_b32_e32 v114, v199, v114, vcc
	v_cmp_lt_i32_e32 vcc, 0, v207
	s_nop 1
	v_cndmask_b32_e32 v99, v199, v99, vcc
	v_cmp_lt_i32_e32 vcc, 32, v207
	s_nop 1
	v_cndmask_b32_e32 v115, v199, v115, vcc
	v_cmp_lt_i32_e32 vcc, 1, v207
	s_nop 1
	v_cndmask_b32_e32 v100, v199, v100, vcc
	v_cmp_lt_i32_e32 vcc, 33, v207
	s_nop 1
	v_cndmask_b32_e32 v116, v199, v116, vcc
	v_cmp_lt_i32_e32 vcc, 2, v207
	s_nop 1
	v_cndmask_b32_e32 v101, v199, v101, vcc
	v_cmp_lt_i32_e32 vcc, 34, v207
	s_nop 1
	v_cndmask_b32_e32 v117, v199, v117, vcc
	v_cmp_lt_i32_e32 vcc, 7, v207
	s_nop 1
	v_cndmask_b32_e32 v102, v199, v102, vcc
	v_cmp_lt_i32_e32 vcc, 39, v207
	s_nop 1
	v_cndmask_b32_e32 v118, v199, v118, vcc
	v_cmp_lt_i32_e32 vcc, 8, v207
	s_nop 1
	v_cndmask_b32_e32 v103, v199, v103, vcc
	v_cmp_lt_i32_e32 vcc, 40, v207
	s_nop 1
	v_cndmask_b32_e32 v119, v199, v119, vcc
	v_cmp_lt_i32_e32 vcc, 9, v207
	s_nop 1
	v_cndmask_b32_e32 v104, v199, v104, vcc
	v_cmp_lt_i32_e32 vcc, 41, v207
	s_nop 1
	v_cndmask_b32_e32 v120, v199, v120, vcc
	v_cmp_lt_i32_e32 vcc, 10, v207
	s_nop 1
	v_cndmask_b32_e32 v105, v199, v105, vcc
	v_cmp_lt_i32_e32 vcc, 42, v207
	s_nop 1
	v_cndmask_b32_e32 v121, v199, v121, vcc
	v_cmp_lt_i32_e32 vcc, 15, v207
	s_nop 1
	v_cndmask_b32_e32 v106, v199, v106, vcc
	v_cmp_lt_i32_e32 vcc, 47, v207
	s_nop 1
	v_cndmask_b32_e32 v122, v199, v122, vcc
	v_cmp_lt_i32_e32 vcc, 16, v207
	s_nop 1
	v_cndmask_b32_e32 v107, v199, v107, vcc
	v_cmp_lt_i32_e32 vcc, 48, v207
	s_nop 1
	v_cndmask_b32_e32 v123, v199, v123, vcc
	v_cmp_lt_i32_e32 vcc, 17, v207
	s_nop 1
	v_cndmask_b32_e32 v108, v199, v108, vcc
	v_cmp_lt_i32_e32 vcc, 49, v207
	s_nop 1
	v_cndmask_b32_e32 v124, v199, v124, vcc
	v_cmp_lt_i32_e32 vcc, 18, v207
	s_nop 1
	v_cndmask_b32_e32 v109, v199, v109, vcc
	v_cmp_lt_i32_e32 vcc, 50, v207
	s_nop 1
	v_cndmask_b32_e32 v125, v199, v125, vcc
	v_cmp_lt_i32_e32 vcc, 23, v207
	s_nop 1
	v_cndmask_b32_e32 v110, v199, v110, vcc
	v_cmp_lt_i32_e32 vcc, 55, v207
	s_nop 1
	v_cndmask_b32_e32 v126, v199, v126, vcc
	v_cmp_lt_i32_e32 vcc, 24, v207
	s_nop 1
	v_cndmask_b32_e32 v111, v199, v111, vcc
	v_cmp_lt_i32_e32 vcc, 56, v207
	s_nop 1
	v_cndmask_b32_e32 v127, v199, v127, vcc
	v_cmp_lt_i32_e32 vcc, 25, v207
	s_nop 1
	v_cndmask_b32_e32 v112, v199, v112, vcc
	v_cmp_lt_i32_e32 vcc, 57, v207
	s_nop 1
	v_cndmask_b32_e32 v128, v199, v128, vcc
	v_cmp_lt_i32_e32 vcc, 26, v207
	s_nop 1
	v_cndmask_b32_e32 v113, v199, v113, vcc
	v_cmp_lt_i32_e32 vcc, 58, v207
	s_nop 1
	v_cndmask_b32_e32 v129, v199, v129, vcc
	s_branch .LBB0_283
; DI float ex2(float x) { return __builtin_amdgcn_exp2f(x); }
; DI float lg2(float x) { return __builtin_amdgcn_logf(x); }
; DI void diff_softmax_pv(const bf16x8 (&qf)[4], const u16* Ks, const u16* Vs, float& m, f32x4& ls0, f32x4& ls1, bf16x8 ones,
;                         f32x16 (&o)[2][2], float sl2, int dl, bool need_mask, bool first, int r, int h, int rs, const int (&lo)[4]) {
;     ...
;     if (__any(first || !(ls0[0] <= 1.0e12f) || !(ls0[1] <= 1.0e12f) || !(ls1[0] <= 1.0e12f) || !(ls1[1] <= 1.0e12f))) {
;       float tmax = -INFINITY;
; #pragma unroll
;       for (int i = 0; i < 16; ++i) tmax = fmaxf(tmax, fmaxf(s0[i], s1[i]));
;       tmax = fmaxf(tmax, shx(tmax, r + 32 * h));
;       const float lmx = fmaxf(own_rowsum(ls0, r), own_rowsum(ls1, r));
;       const float lref = (lmx > 1.f) ? lg2(lmx) : 0.f;
;       const float delta = first ? tmax : fmaxf(fmaxf(tmax, lref), 0.f);
;       m += delta;
;       const float alpha = ex2(-delta);
;       const float alpha_hi = shx(alpha, r + 32 * h, 16);
;       ls0[0] *= alpha; ls0[1] *= alpha_hi; ls1[0] *= alpha; ls1[1] *= alpha_hi;
; #pragma unroll
;       for (int e = 0; e < 16; ++e) {
;         o[0][0][e] *= alpha; o[0][1][e] *= alpha; o[1][0][e] *= alpha; o[1][1][e] *= alpha;
;         s0[e] -= delta; s1[e] -= delta; b0[e] -= delta; b1[e] -= delta;
;       }
;     }
.Lresc_ool:
	v_max_f32_e32 v214, v114, v114
	v_max_f32_e32 v215, v98, v98
	v_max_f32_e32 v214, v215, v214
	v_max_f32_e32 v215, v115, v115
	v_max_f32_e32 v216, v99, v99
	v_max_f32_e32 v215, v216, v215
	s_mov_b32 s2, 0xff800000
	v_max3_f32 v214, v214, s2, v215
	v_max_f32_e32 v215, v116, v116
	v_max_f32_e32 v216, v100, v100
	v_max_f32_e32 v215, v216, v215
	v_max_f32_e32 v216, v117, v117
	v_max_f32_e32 v217, v101, v101
	v_max_f32_e32 v216, v217, v216
	v_max3_f32 v214, v214, v215, v216
	v_max_f32_e32 v215, v118, v118
	v_max_f32_e32 v216, v102, v102
	v_max_f32_e32 v215, v216, v215
	v_max_f32_e32 v216, v119, v119
	v_max_f32_e32 v217, v103, v103
	v_max_f32_e32 v216, v217, v216
	v_max3_f32 v214, v214, v215, v216
	v_max_f32_e32 v215, v120, v120
	v_max_f32_e32 v216, v104, v104
	v_max_f32_e32 v215, v216, v215
	v_max_f32_e32 v216, v121, v121
	v_max_f32_e32 v217, v105, v105
	v_max_f32_e32 v216, v217, v216
	v_max3_f32 v214, v214, v215, v216
	v_max_f32_e32 v215, v122, v122
	v_max_f32_e32 v216, v106, v106
	v_max_f32_e32 v215, v216, v215
	v_max_f32_e32 v216, v123, v123
	v_max_f32_e32 v217, v107, v107
	v_max_f32_e32 v216, v217, v216
	v_max3_f32 v214, v214, v215, v216
	v_max_f32_e32 v215, v124, v124
	v_max_f32_e32 v216, v108, v108
	v_max_f32_e32 v215, v216, v215
	v_max_f32_e32 v216, v125, v125
	v_max_f32_e32 v217, v109, v109
	v_max_f32_e32 v216, v217, v216
	v_max3_f32 v214, v214, v215, v216
	v_max_f32_e32 v215, v126, v126
	v_max_f32_e32 v216, v110, v110
	v_max_f32_e32 v215, v216, v215
	v_max_f32_e32 v216, v127, v127
	v_max_f32_e32 v217, v111, v111
	v_max_f32_e32 v216, v217, v216
	v_max3_f32 v214, v214, v215, v216
	v_max_f32_e32 v215, v128, v128
	v_max_f32_e32 v216, v112, v112
	v_max_f32_e32 v215, v216, v215
	v_max_f32_e32 v216, v129, v129
	v_max_f32_e32 v217, v113, v113
	v_max_f32_e32 v216, v217, v216
	v_max3_f32 v214, v214, v215, v216
	ds_bpermute_b32 v215, v181, v214
	ds_bpermute_b32 v216, v205, v151
	ds_bpermute_b32 v217, v205, v155
	s_waitcnt lgkmcnt(2)
	v_max_f32_e32 v215, v215, v215
	v_max_f32_e32 v214, v214, v215
	ds_bpermute_b32 v215, v205, v150
	s_waitcnt lgkmcnt(0)
	v_cndmask_b32_e64 v215, v216, v215, s[36:37]
	ds_bpermute_b32 v216, v205, v154
	v_max_f32_e32 v215, v215, v215
	s_waitcnt lgkmcnt(0)
	v_cndmask_b32_e64 v216, v217, v216, s[36:37]
	v_max_f32_e32 v216, v216, v216
	v_max_f32_e32 v215, v215, v216
	v_cmp_lt_f32_e32 vcc, 1.0, v215
	v_log_f32_e32 v215, v215
	s_nop 0
	v_cndmask_b32_e32 v215, 0, v215, vcc
	v_max3_f32 v215, v214, v215, 0
	v_cndmask_b32_e64 v216, v214, v215, s[42:43]
	v_exp_f32_e64 v214, -v216
	v_add_f32_e32 v204, v204, v216
	v_sub_f32_e32 v113, v113, v216
	v_sub_f32_e32 v112, v112, v216
	ds_bpermute_b32 v215, v182, v214
	v_sub_f32_e32 v111, v111, v216
	v_sub_f32_e32 v110, v110, v216
	v_sub_f32_e32 v109, v109, v216
	v_sub_f32_e32 v108, v108, v216
	s_waitcnt lgkmcnt(0)
	v_pk_mul_f32 v[150:151], v[150:151], v[214:215]
	v_pk_mul_f32 v[154:155], v[154:155], v[214:215]
	v_pk_mul_f32 v[16:17], v[16:17], v[214:215] op_sel_hi:[1,0]
	v_pk_mul_f32 v[14:15], v[14:15], v[214:215] op_sel_hi:[1,0]
	v_pk_mul_f32 v[12:13], v[12:13], v[214:215] op_sel_hi:[1,0]
	v_pk_mul_f32 v[10:11], v[10:11], v[214:215] op_sel_hi:[1,0]
	v_pk_mul_f32 v[8:9], v[8:9], v[214:215] op_sel_hi:[1,0]
	v_pk_mul_f32 v[6:7], v[6:7], v[214:215] op_sel_hi:[1,0]
	v_pk_mul_f32 v[4:5], v[4:5], v[214:215] op_sel_hi:[1,0]
	v_pk_mul_f32 v[2:3], v[2:3], v[214:215] op_sel_hi:[1,0]
	v_pk_mul_f32 v[48:49], v[48:49], v[214:215] op_sel_hi:[1,0]
	v_pk_mul_f32 v[46:47], v[46:47], v[214:215] op_sel_hi:[1,0]
	v_pk_mul_f32 v[44:45], v[44:45], v[214:215] op_sel_hi:[1,0]
	v_pk_mul_f32 v[42:43], v[42:43], v[214:215] op_sel_hi:[1,0]
	v_pk_mul_f32 v[40:41], v[40:41], v[214:215] op_sel_hi:[1,0]
	v_pk_mul_f32 v[38:39], v[38:39], v[214:215] op_sel_hi:[1,0]
	v_pk_mul_f32 v[36:37], v[36:37], v[214:215] op_sel_hi:[1,0]
	v_pk_mul_f32 v[34:35], v[34:35], v[214:215] op_sel_hi:[1,0]
	v_pk_mul_f32 v[64:65], v[64:65], v[214:215] op_sel_hi:[1,0]
	v_pk_mul_f32 v[62:63], v[62:63], v[214:215] op_sel_hi:[1,0]
	v_pk_mul_f32 v[60:61], v[60:61], v[214:215] op_sel_hi:[1,0]
	v_pk_mul_f32 v[58:59], v[58:59], v[214:215] op_sel_hi:[1,0]
	v_pk_mul_f32 v[56:57], v[56:57], v[214:215] op_sel_hi:[1,0]
	v_pk_mul_f32 v[54:55], v[54:55], v[214:215] op_sel_hi:[1,0]
	v_pk_mul_f32 v[52:53], v[52:53], v[214:215] op_sel_hi:[1,0]
	v_pk_mul_f32 v[50:51], v[50:51], v[214:215] op_sel_hi:[1,0]
	v_pk_mul_f32 v[32:33], v[32:33], v[214:215] op_sel_hi:[1,0]
	v_pk_mul_f32 v[30:31], v[30:31], v[214:215] op_sel_hi:[1,0]
	v_pk_mul_f32 v[28:29], v[28:29], v[214:215] op_sel_hi:[1,0]
	v_pk_mul_f32 v[26:27], v[26:27], v[214:215] op_sel_hi:[1,0]
	v_pk_mul_f32 v[24:25], v[24:25], v[214:215] op_sel_hi:[1,0]
	v_pk_mul_f32 v[22:23], v[22:23], v[214:215] op_sel_hi:[1,0]
	v_pk_mul_f32 v[20:21], v[20:21], v[214:215] op_sel_hi:[1,0]
	v_pk_mul_f32 v[18:19], v[18:19], v[214:215] op_sel_hi:[1,0]
	v_sub_f32_e32 v107, v107, v216
	v_sub_f32_e32 v106, v106, v216
	v_sub_f32_e32 v105, v105, v216
	v_sub_f32_e32 v104, v104, v216
	v_sub_f32_e32 v103, v103, v216
	v_sub_f32_e32 v102, v102, v216
	v_sub_f32_e32 v101, v101, v216
	v_sub_f32_e32 v100, v100, v216
	v_sub_f32_e32 v99, v99, v216
	v_sub_f32_e32 v98, v98, v216
	v_sub_f32_e32 v129, v129, v216
	v_sub_f32_e32 v128, v128, v216
	v_sub_f32_e32 v127, v127, v216
	v_sub_f32_e32 v126, v126, v216
	v_sub_f32_e32 v125, v125, v216
	v_sub_f32_e32 v124, v124, v216
	v_sub_f32_e32 v123, v123, v216
	v_sub_f32_e32 v122, v122, v216
	v_sub_f32_e32 v121, v121, v216
	v_sub_f32_e32 v120, v120, v216
	v_sub_f32_e32 v119, v119, v216
	v_sub_f32_e32 v118, v118, v216
	v_sub_f32_e32 v117, v117, v216
	v_sub_f32_e32 v116, v116, v216
	v_sub_f32_e32 v115, v115, v216
	v_sub_f32_e32 v114, v114, v216
	v_sub_f32_e32 v81, v81, v216
	v_sub_f32_e32 v80, v80, v216
	v_sub_f32_e32 v79, v79, v216
	v_sub_f32_e32 v78, v78, v216
	v_sub_f32_e32 v77, v77, v216
	v_sub_f32_e32 v76, v76, v216
	v_sub_f32_e32 v75, v75, v216
	v_sub_f32_e32 v74, v74, v216
	v_sub_f32_e32 v73, v73, v216
	v_sub_f32_e32 v72, v72, v216
	v_sub_f32_e32 v71, v71, v216
	v_sub_f32_e32 v70, v70, v216
	v_sub_f32_e32 v69, v69, v216
	v_sub_f32_e32 v68, v68, v216
	v_sub_f32_e32 v67, v67, v216
	v_sub_f32_e32 v66, v66, v216
	v_sub_f32_e32 v82, v82, v216
	v_sub_f32_e32 v83, v83, v216
	v_sub_f32_e32 v84, v84, v216
	v_sub_f32_e32 v85, v85, v216
	v_sub_f32_e32 v86, v86, v216
	v_sub_f32_e32 v87, v87, v216
	v_sub_f32_e32 v88, v88, v216
	v_sub_f32_e32 v89, v89, v216
	v_sub_f32_e32 v90, v90, v216
	v_sub_f32_e32 v91, v91, v216
	v_sub_f32_e32 v92, v92, v216
	v_sub_f32_e32 v93, v93, v216
	v_sub_f32_e32 v94, v94, v216
	v_sub_f32_e32 v95, v95, v216
	v_sub_f32_e32 v96, v96, v216
	v_sub_f32_e32 v97, v97, v216
	s_branch .LBB0_289
